# P0 weight conversion balanced: 2 full rounds in the compiler loop + left-over 320 w_down tiles as 1280 per-wave quarter tiles from registers (no LDS)
# speedup vs baseline: 1.0002x; 1.0002x over previous
; #define LAS __attribute__((address_space(3)))
; __device__ __forceinline__ void p0_convert(const Args& a, LAS float* scr, int gw, int NGW, int lane) {
;     constexpr int I_IN = 104 * 16, I_PA = 16 * 8, I_PB = 16 * 16, I_OUT = 16 * 16, I_GU = 88 * 16, I_DN = 16 * 44, TOTAL = I_IN + I_PA + I_PB + I_OUT + I_GU + I_DN;
;     for (int it = gw; it < TOTAL; it += NGW) {
;         int r = it, kind, K; size_t dsto;
;         if (r < I_IN) { kind = 0; K = 1024; dsto = WS_WIN; }
;         else if ((r -= I_IN) < I_PA) { kind = 1; K = 512; dsto = WS_WPA; }
;         else if ((r -= I_PA) < I_PB) { kind = 2; K = 1024; dsto = WS_WPB; }
;         else if ((r -= I_PB) < I_OUT) { kind = 3; K = 1024; dsto = WS_WOUT; }
;         else if ((r -= I_OUT) < I_GU) { kind = 4; K = 1024; dsto = WS_WGU; }
;         else { r -= I_GU; kind = 5; K = 2816; dsto = WS_WDN; }
;         const int ktiles = K >> 6, n0 = (r / ktiles) * 64, k0 = (r % ktiles) * 64, n = n0 + lane;
.LBB0_88:
	s_or_b64 exec, exec, s[6:7]
	s_cmpk_gt_i32 s81, 0x113f
	s_cbranch_scc1 .LBB0_129
	v_and_b32_e32 v0, 31, v178
	s_mul_i32 s0, s93, 0x4100
	v_lshlrev_b32_e32 v5, 3, v0
	v_lshlrev_b32_e32 v0, 2, v0
	v_mov_b32_e32 v1, 0
	s_movk_i32 s6, 0x104
	v_lshrrev_b32_e32 v20, 5, v176
	v_lshl_add_u64 v[2:3], s[54:55], 0, v[0:1]
	v_mov_b32_e32 v0, s0
	s_add_i32 s3, s0, 0
	v_mul_u32_u24_e32 v4, 0x104, v176
	v_mad_u32_u24 v0, v20, s6, v0
	s_mov_b32 s1, 0
	v_or_b32_e32 v21, 14, v20
	v_add3_u32 v22, v0, v5, 0
	v_or_b32_e32 v23, 12, v20
	v_or_b32_e32 v24, 10, v20
	v_or_b32_e32 v25, 8, v20
	v_or_b32_e32 v26, 6, v20
	v_or_b32_e32 v27, 4, v20
	v_or_b32_e32 v28, 2, v20
	s_movk_i32 s72, 0x1200
	v_add_u32_e32 v29, s3, v4
	s_xor_b32 s73, s81, 0x400
	s_movk_i32 s98, 0x113f
	s_cmpk_eq_i32 s58, 0x100
	s_cselect_b32 s98, 0xfff, s98

; __device__ __forceinline__ unsigned cvt_pk_bf16(float lo, float hi) { f32x2 v = {lo, hi}; bf16x2_t b = __builtin_convertvector(v, bf16x2_t); return __builtin_bit_cast(unsigned, b); }
; __device__ __forceinline__ void wave_lds_sync() { asm volatile("s_waitcnt lgkmcnt(0)" ::: "memory"); __builtin_amdgcn_wave_barrier(); }
; __device__ __forceinline__ void p0_convert(const Args& a, LAS float* scr, int gw, int NGW, int lane) {
;     ...
;     for (int it = gw; it < TOTAL; it += NGW) {
;     ...
;         unsigned* dst = (unsigned*)(a.ws + dsto) + ((size_t)n0 * K + k0) / 2 + (lane & 31);
; #pragma unroll 8
;         for (int j = 0; j < 32; ++j) { const int row = 2 * j + (lane >> 5), kk = (lane & 31) * 2; dst[(size_t)row * (K / 2)] = cvt_pk_bf16(scr[row * 65 + kk], scr[row * 65 + kk + 1]); }
;         wave_lds_sync();
;     }
.LBB0_126:
	v_add_u32_e32 v0, s0, v22
	v_add_u32_e32 v50, 0x410, v0
	v_add_u32_e32 v52, 0x618, v0
	v_add_u32_e32 v54, 0x820, v0
	v_add_u32_e32 v56, 0xa28, v0
	v_add_u32_e32 v58, 0xc30, v0
	v_add_u32_e32 v60, 0xe38, v0
	ds_read2_b32 v[46:47], v0 offset1:1
	ds_read2_b32 v[48:49], v0 offset0:130 offset1:131
	ds_read2_b32 v[50:51], v50 offset1:1
	ds_read2_b32 v[52:53], v52 offset1:1
	ds_read2_b32 v[54:55], v54 offset1:1
	ds_read2_b32 v[56:57], v56 offset1:1
	ds_read2_b32 v[58:59], v58 offset1:1
	ds_read2_b32 v[60:61], v60 offset1:1
	v_lshl_add_u64 v[30:31], v[18:19], 0, s[8:9]
	s_addk_i32 s0, 0x1040
	s_waitcnt lgkmcnt(0)
	v_cvt_pk_bf16_f32 v0, v46, v47
	v_lshl_add_u64 v[32:33], v[16:17], 0, s[8:9]
	v_lshl_add_u64 v[34:35], v[14:15], 0, s[8:9]
	v_lshl_add_u64 v[36:37], v[12:13], 0, s[8:9]
	v_lshl_add_u64 v[38:39], v[10:11], 0, s[8:9]
	v_lshl_add_u64 v[40:41], v[8:9], 0, s[8:9]
	v_lshl_add_u64 v[42:43], v[6:7], 0, s[8:9]
	v_lshl_add_u64 v[44:45], v[4:5], 0, s[8:9]
	v_lshl_add_u64 v[4:5], v[4:5], 0, s[10:11]
	v_lshl_add_u64 v[6:7], v[6:7], 0, s[10:11]
	v_lshl_add_u64 v[8:9], v[8:9], 0, s[10:11]
	v_lshl_add_u64 v[10:11], v[10:11], 0, s[10:11]
	v_lshl_add_u64 v[12:13], v[12:13], 0, s[10:11]
	v_lshl_add_u64 v[14:15], v[14:15], 0, s[10:11]
	v_lshl_add_u64 v[16:17], v[16:17], 0, s[10:11]
	v_lshl_add_u64 v[18:19], v[18:19], 0, s[10:11]
	s_cmpk_eq_i32 s0, 0x4100
	v_cvt_pk_bf16_f32 v46, v48, v49
	global_store_dword v[30:31], v0, off
	global_store_dword v[32:33], v46, off
	v_cvt_pk_bf16_f32 v0, v50, v51
	v_cvt_pk_bf16_f32 v30, v52, v53
	v_cvt_pk_bf16_f32 v31, v54, v55
	v_cvt_pk_bf16_f32 v32, v56, v57
	v_cvt_pk_bf16_f32 v33, v58, v59
	v_cvt_pk_bf16_f32 v46, v60, v61
	global_store_dword v[34:35], v0, off
	global_store_dword v[36:37], v30, off
	global_store_dword v[38:39], v31, off
	global_store_dword v[40:41], v32, off
	global_store_dword v[42:43], v33, off
	global_store_dword v[44:45], v46, off
	s_cbranch_scc0 .LBB0_126
	s_waitcnt lgkmcnt(0)
	s_add_i32 s73, s73, s96
	s_cmp_gt_i32 s73, s98
	s_cbranch_scc0 .LBB0_90
	s_branch .LBB0_129

; __device__ __forceinline__ unsigned cvt_pk_bf16(float lo, float hi) { f32x2 v = {lo, hi}; bf16x2_t b = __builtin_convertvector(v, bf16x2_t); return __builtin_bit_cast(unsigned, b); }
; __device__ __forceinline__ void wave_lds_sync() { asm volatile("s_waitcnt lgkmcnt(0)" ::: "memory"); __builtin_amdgcn_wave_barrier(); }
; __device__ __forceinline__ void p0_convert(const Args& a, LAS float* scr, int gw, int NGW, int lane) {
;     ...
;         const int ktiles = K >> 6, n0 = (r / ktiles) * 64, k0 = (r % ktiles) * 64, n = n0 + lane;
;         const float* sp; int srcN;
;         if (kind == 0) { sp = a.in[I_WIN] + (n < 4608 ? n : n + 16); srcN = DIN; }
;         else if (kind == 1) { sp = a.in[I_WPA] + n; srcN = 1024; }
;         else if (kind == 2) { sp = a.in[I_WPB] + n; srcN = 1024; }
;         else if (kind == 3) { sp = a.in[I_WOUT] + n; srcN = 1024; }
;         else if (kind == 4) { const int pn = n >> 8, rr = n & 255; sp = ((rr < 128) ? a.in[I_WG] : a.in[I_WU]) + 128 * pn + (rr & 127); srcN = DFF; }
;         else { sp = a.in[I_WD] + n; srcN = 1024; }
;         sp += (size_t)k0 * srcN;
;         float tmp[64];
; #pragma unroll
;         for (int i = 0; i < 64; ++i) tmp[i] = sp[(size_t)i * srcN];
; #pragma unroll
;         for (int i = 0; i < 64; ++i) scr[lane * 65 + i] = tmp[i];
;         wave_lds_sync();
;         unsigned* dst = (unsigned*)(a.ws + dsto) + ((size_t)n0 * K + k0) / 2 + (lane & 31);
; #pragma unroll 8
;         for (int j = 0; j < 32; ++j) { const int row = 2 * j + (lane >> 5), kk = (lane & 31) * 2; dst[(size_t)row * (K / 2)] = cvt_pk_bf16(scr[row * 65 + kk], scr[row * 65 + kk + 1]); }
; __device__ __forceinline__ void p0_rows(const Args& a, LAS unsigned char* lds, int gw, int NGW, int wave, int lane, int tid) {
;     ...
;     for (int idx = tid; idx < 1024 * 16; idx += 512) { const int k = idx >> 4, j = idx & 15; WdL[(k >> 8) * 4112 + (k & 255) * 16 + j] = a.in[I_WIN][(size_t)k * DIN + 4608 + j]; }
;     __syncthreads();
;     bf16_t* H = (bf16_t*)((unsigned char*)a.out + Y_H); float* DLR = (float*)((unsigned char*)a.out + Y_DLR);
;     const f32x4* gp = (const f32x4*)a.in[I_NMPRE] + lane; f32x4 g[4];
; #pragma unroll
;     for (int j = 0; j < 4; ++j) g[j] = gp[64 * j];
;     for (int row = gw; row < MT; row += NGW) {
;         const f32x4* xr = (const f32x4*)xrow_ptr(a, row) + lane; f32x4 v[4]; float s = 0.f;
.LBB0_129:
	s_cmpk_lg_i32 s58, 0x100
	s_cbranch_scc1 .Lp0m_generic
	s_cmpk_gt_i32 s81, 0x4ff
	s_cbranch_scc1 .Lp0q_done
	s_lshr_b32 s0, s81, 2
	s_addk_i32 s0, 0x180
	s_and_b32 s1, s81, 3
	s_mul_hi_u32 s3, s0, 0x5d1745e
	s_mul_i32 s6, s3, 44
	s_sub_i32 s6, s0, s6
	s_lshl_b32 s6, s6, 6
	s_lshl_b32 s7, s1, 4
	s_add_i32 s6, s6, s7
	s_lshl_b32 s3, s3, 6
	s_lshl_b32 s7, s6, 12
	s_lshl_b32 s8, s3, 2
	s_add_u32 s7, s7, s8
	s_add_u32 s8, s66, s7
	s_addc_u32 s9, s67, 0
	v_lshlrev_b32_e32 v0, 2, v176
	global_load_dword v1, v0, s[8:9]
	s_add_u32 s8, s8, 0x1000
	s_addc_u32 s9, s9, 0
	global_load_dword v2, v0, s[8:9]
	s_add_u32 s8, s8, 0x1000
	s_addc_u32 s9, s9, 0
	global_load_dword v3, v0, s[8:9]
	s_add_u32 s8, s8, 0x1000
	s_addc_u32 s9, s9, 0
	global_load_dword v4, v0, s[8:9]
	s_add_u32 s8, s8, 0x1000
	s_addc_u32 s9, s9, 0
	global_load_dword v5, v0, s[8:9]
	s_add_u32 s8, s8, 0x1000
	s_addc_u32 s9, s9, 0
	global_load_dword v6, v0, s[8:9]
	s_add_u32 s8, s8, 0x1000
	s_addc_u32 s9, s9, 0
	global_load_dword v7, v0, s[8:9]
	s_add_u32 s8, s8, 0x1000
	s_addc_u32 s9, s9, 0
	global_load_dword v8, v0, s[8:9]
	s_add_u32 s8, s8, 0x1000
	s_addc_u32 s9, s9, 0
	global_load_dword v9, v0, s[8:9]
	s_add_u32 s8, s8, 0x1000
	s_addc_u32 s9, s9, 0
	global_load_dword v10, v0, s[8:9]
	s_add_u32 s8, s8, 0x1000
	s_addc_u32 s9, s9, 0
	global_load_dword v11, v0, s[8:9]
	s_add_u32 s8, s8, 0x1000
	s_addc_u32 s9, s9, 0
	global_load_dword v12, v0, s[8:9]
	s_add_u32 s8, s8, 0x1000
	s_addc_u32 s9, s9, 0
	global_load_dword v13, v0, s[8:9]
	s_add_u32 s8, s8, 0x1000
	s_addc_u32 s9, s9, 0
	global_load_dword v14, v0, s[8:9]
	s_add_u32 s8, s8, 0x1000
	s_addc_u32 s9, s9, 0
	global_load_dword v15, v0, s[8:9]
	s_add_u32 s8, s8, 0x1000
	s_addc_u32 s9, s9, 0
	global_load_dword v16, v0, s[8:9]
	s_mul_i32 s10, s3, 0x1600
	s_lshl_b32 s11, s6, 1
	s_add_u32 s10, s10, s11
	s_add_u32 s10, s54, s10
	s_addc_u32 s11, s55, 0
	s_add_u32 s10, s10, 0x1d00000
	s_addc_u32 s11, s11, 0
	v_mul_u32_u24_e32 v17, 0x1600, v176
	s_waitcnt vmcnt(14)
	v_cvt_pk_bf16_f32 v18, v1, v2
	s_waitcnt vmcnt(12)
	v_cvt_pk_bf16_f32 v19, v3, v4
	s_waitcnt vmcnt(10)
	v_cvt_pk_bf16_f32 v20, v5, v6
	s_waitcnt vmcnt(8)
	v_cvt_pk_bf16_f32 v21, v7, v8
	s_waitcnt vmcnt(6)
	v_cvt_pk_bf16_f32 v22, v9, v10
	s_waitcnt vmcnt(4)
	v_cvt_pk_bf16_f32 v23, v11, v12
	s_waitcnt vmcnt(2)
	v_cvt_pk_bf16_f32 v24, v13, v14
	s_waitcnt vmcnt(0)
	v_cvt_pk_bf16_f32 v25, v15, v16
	global_store_dwordx4 v17, v[18:21], s[10:11]
	global_store_dwordx4 v17, v[22:25], s[10:11] offset:16
.Lp0q_done:
	v_lshlrev_b32_e32 v28, 4, v176
	v_lshlrev_b32_e32 v29, 3, v176
	v_mov_b32_e32 v16, 0x358637bd
	v_mov_b32_e32 v17, v28
	v_and_b32_e32 v30, 15, v176
	v_lshrrev_b32_e32 v31, 4, v176
	v_readlane_b32 s36, v252, 1
	v_readlane_b32 s37, v252, 2
	v_readlane_b32 s38, v252, 3
	v_readlane_b32 s39, v252, 4
	v_readlane_b32 s46, v252, 11
	v_readlane_b32 s47, v252, 12
	s_mov_b32 s3, 0x800000
	s_mul_i32 s42, s93, 0x1010
	s_nop 4
	global_load_dwordx4 v[0:3], v28, s[46:47]
	global_load_dwordx4 v[4:7], v28, s[46:47] offset:1024
	global_load_dwordx4 v[8:11], v28, s[46:47] offset:2048
	global_load_dwordx4 v[12:15], v28, s[46:47] offset:3072
	s_lshl_b32 s10, s81, 12
	s_add_u32 s44, s36, s10
	s_addc_u32 s45, s37, 0
	global_load_dwordx4 v[32:35], v28, s[44:45]
	global_load_dwordx4 v[36:39], v28, s[44:45] offset:1024
	global_load_dwordx4 v[40:43], v28, s[44:45] offset:2048
	global_load_dwordx4 v[44:47], v28, s[44:45] offset:3072
	s_add_u32 s10, s44, 0x800000
	s_addc_u32 s11, s45, 0
	global_load_dwordx4 v[48:51], v28, s[10:11]
	global_load_dwordx4 v[52:55], v28, s[10:11] offset:1024
	global_load_dwordx4 v[56:59], v28, s[10:11] offset:2048
	global_load_dwordx4 v[60:63], v28, s[10:11] offset:3072
	s_lshl_b32 s10, s81, 11
	s_add_u32 s40, s52, s10
	s_addc_u32 s41, s53, 0
	v_lshlrev_b32_e32 v24, 8, v31
	s_lshl_b32 s10, s93, 5
	v_add_u32_e32 v24, s10, v24
	v_mul_u32_u24_e32 v24, 0x1a10, v24
	v_add_u32_e32 v24, v24, v30
	v_add_u32_e32 v24, 0x1200, v24
	v_lshlrev_b32_e32 v24, 2, v24
	s_mov_b64 s[0:1], s[14:15]
	global_load_dword v96, v24, s[0:1]
	s_add_u32 s0, s0, 0x6840
	s_addc_u32 s1, s1, 0
	global_load_dword v97, v24, s[0:1]
	s_add_u32 s0, s0, 0x6840
	s_addc_u32 s1, s1, 0
	global_load_dword v98, v24, s[0:1]
	s_add_u32 s0, s0, 0x6840
	s_addc_u32 s1, s1, 0
	global_load_dword v99, v24, s[0:1]
	s_add_u32 s0, s0, 0x6840
	s_addc_u32 s1, s1, 0
	global_load_dword v100, v24, s[0:1]
	s_add_u32 s0, s0, 0x6840
	s_addc_u32 s1, s1, 0
	global_load_dword v101, v24, s[0:1]
	s_add_u32 s0, s0, 0x6840
	s_addc_u32 s1, s1, 0
	global_load_dword v102, v24, s[0:1]
	s_add_u32 s0, s0, 0x6840
	s_addc_u32 s1, s1, 0
	global_load_dword v103, v24, s[0:1]
	s_add_u32 s0, s0, 0x6840
	s_addc_u32 s1, s1, 0
	global_load_dword v104, v24, s[0:1]
	s_add_u32 s0, s0, 0x6840
	s_addc_u32 s1, s1, 0
	global_load_dword v105, v24, s[0:1]
	s_add_u32 s0, s0, 0x6840
	s_addc_u32 s1, s1, 0
	global_load_dword v106, v24, s[0:1]
	s_add_u32 s0, s0, 0x6840
	s_addc_u32 s1, s1, 0
	global_load_dword v107, v24, s[0:1]
	s_add_u32 s0, s0, 0x6840
	s_addc_u32 s1, s1, 0
	global_load_dword v108, v24, s[0:1]
	s_add_u32 s0, s0, 0x6840
	s_addc_u32 s1, s1, 0
	global_load_dword v109, v24, s[0:1]
	s_add_u32 s0, s0, 0x6840
	s_addc_u32 s1, s1, 0
	global_load_dword v110, v24, s[0:1]
	s_add_u32 s0, s0, 0x6840
	s_addc_u32 s1, s1, 0
	global_load_dword v111, v24, s[0:1]
	s_add_u32 s0, s0, 0x6840
	s_addc_u32 s1, s1, 0
	global_load_dword v112, v24, s[0:1]
	s_add_u32 s0, s0, 0x6840
	s_addc_u32 s1, s1, 0
	global_load_dword v113, v24, s[0:1]
	s_add_u32 s0, s0, 0x6840
	s_addc_u32 s1, s1, 0
	global_load_dword v114, v24, s[0:1]
	s_add_u32 s0, s0, 0x6840
	s_addc_u32 s1, s1, 0
; #define LAS __attribute__((address_space(3)))
; __device__ __forceinline__ float wave_sum(float v) { for (int o = 32; o >= 1; o >>= 1) v += __shfl_xor(v, o); return v; }
; __device__ __forceinline__ u32x2 pk4(f32x4 v) { u32x2 w; w.x = cvt_pk_bf16(v[0], v[1]); w.y = cvt_pk_bf16(v[2], v[3]); return w; }
; __device__ __forceinline__ void p0_rows(const Args& a, LAS unsigned char* lds, int gw, int NGW, int wave, int lane, int tid) {
;     ...
;     for (int j = 0; j < 4; ++j) g[j] = gp[64 * j];
;     for (int row = gw; row < MT; row += NGW) {
;         const f32x4* xr = (const f32x4*)xrow_ptr(a, row) + lane; f32x4 v[4]; float s = 0.f;
; #pragma unroll
;         for (int j = 0; j < 4; ++j) { v[j] = xr[64 * j]; s += (v[j][0] * v[j][0] + v[j][1] * v[j][1]) + (v[j][2] * v[j][2] + v[j][3] * v[j][3]); }
;         const float rstd = rsqrtf(wave_sum(s) * (1.f / DM) + EPS);
;         u32x2* ho = (u32x2*)(H + (size_t)row * DM) + lane;
; #pragma unroll
;         for (int j = 0; j < 4; ++j) { v[j] = v[j] * rstd * g[j]; ho[64 * j] = pk4(v[j]); *(LAS f32x4*)(hrow + j * 264 + 4 * lane) = v[j]; }
	global_load_dword v115, v24, s[0:1]
	s_add_u32 s0, s0, 0x6840
	s_addc_u32 s1, s1, 0
	global_load_dword v116, v24, s[0:1]
	s_add_u32 s0, s0, 0x6840
	s_addc_u32 s1, s1, 0
	global_load_dword v117, v24, s[0:1]
	s_add_u32 s0, s0, 0x6840
	s_addc_u32 s1, s1, 0
	global_load_dword v118, v24, s[0:1]
	s_add_u32 s0, s0, 0x6840
	s_addc_u32 s1, s1, 0
	global_load_dword v119, v24, s[0:1]
	s_add_u32 s0, s0, 0x6840
	s_addc_u32 s1, s1, 0
	global_load_dword v120, v24, s[0:1]
	s_add_u32 s0, s0, 0x6840
	s_addc_u32 s1, s1, 0
	global_load_dword v121, v24, s[0:1]
	s_add_u32 s0, s0, 0x6840
	s_addc_u32 s1, s1, 0
	global_load_dword v122, v24, s[0:1]
	s_add_u32 s0, s0, 0x6840
	s_addc_u32 s1, s1, 0
	global_load_dword v123, v24, s[0:1]
	s_add_u32 s0, s0, 0x6840
	s_addc_u32 s1, s1, 0
	global_load_dword v124, v24, s[0:1]
	s_add_u32 s0, s0, 0x6840
	s_addc_u32 s1, s1, 0
	global_load_dword v125, v24, s[0:1]
	s_add_u32 s0, s0, 0x6840
	s_addc_u32 s1, s1, 0
	global_load_dword v126, v24, s[0:1]
	s_add_u32 s0, s0, 0x6840
	s_addc_u32 s1, s1, 0
	global_load_dword v127, v24, s[0:1]
	v_mul_u32_u24_e32 v19, 0x1010, v30
	v_lshlrev_b32_e32 v25, 10, v31
	s_lshl_b32 s10, s93, 7
	v_add3_u32 v19, v19, v25, s10
	v_add_u32_e32 v20, 0x10100, v19
	s_lshl_b32 s10, s93, 10
	s_add_i32 s10, s10, 0x20200
	v_add_u32_e32 v21, s10, v28
	v_and_b32_e32 v25, 3, v31
	s_lshl_b32 s10, s93, 8
	s_add_i32 s10, s10, 0x20200
	v_lshlrev_b32_e32 v22, 4, v30
	v_lshl_add_u32 v22, v25, 2, v22
	v_add_u32_e32 v22, s10, v22
	s_lshl_b32 s10, s93, 2
	v_add_u32_e32 v26, s10, v25
	v_and_b32_e32 v27, 7, v26
	v_lshrrev_b32_e32 v26, 3, v26
	v_lshl_add_u32 v27, v26, 11, v27
	s_lshl_b32 s10, s2, 3
	v_add_u32_e32 v27, s10, v27
	v_lshlrev_b32_e32 v27, 6, v27
	v_lshl_add_u32 v23, v30, 2, v27
	v_add_u32_e32 v23, 0x4000000, v23
	s_waitcnt lgkmcnt(0)
	s_barrier
	s_add_u32 s44, s44, 0x1000000
	s_addc_u32 s45, s45, 0
	global_load_dwordx4 v[192:195], v28, s[44:45]
	global_load_dwordx4 v[196:199], v28, s[44:45] offset:1024
	global_load_dwordx4 v[200:203], v28, s[44:45] offset:2048
	global_load_dwordx4 v[204:207], v28, s[44:45] offset:3072
	s_add_u32 s10, s44, 0x800000
	s_addc_u32 s11, s45, 0
	global_load_dwordx4 v[208:211], v28, s[10:11]
	global_load_dwordx4 v[212:215], v28, s[10:11] offset:1024
	global_load_dwordx4 v[216:219], v28, s[10:11] offset:2048
	global_load_dwordx4 v[220:223], v28, s[10:11] offset:3072
	s_waitcnt vmcnt(40)
	v_mul_f32_e32 v64, v32, v32
	v_fmac_f32_e32 v64, v33, v33
	v_mul_f32_e32 v65, v34, v34
	v_fmac_f32_e32 v65, v35, v35
	v_add_f32_e32 v64, v64, v65
	v_mul_f32_e32 v66, v36, v36
	v_fmac_f32_e32 v66, v37, v37
	v_mul_f32_e32 v67, v38, v38
	v_fmac_f32_e32 v67, v39, v39
	v_add_f32_e32 v66, v66, v67
	v_mul_f32_e32 v68, v40, v40
	v_fmac_f32_e32 v68, v41, v41
	v_mul_f32_e32 v69, v42, v42
	v_fmac_f32_e32 v69, v43, v43
	v_add_f32_e32 v68, v68, v69
	v_mul_f32_e32 v70, v44, v44
	v_fmac_f32_e32 v70, v45, v45
	v_mul_f32_e32 v71, v46, v46
	v_fmac_f32_e32 v71, v47, v47
	v_add_f32_e32 v70, v70, v71
	v_add_f32_e32 v64, v64, v66
	v_add_f32_e32 v64, v64, v68
	v_add_f32_e32 v64, v64, v70
	s_nop 1
	v_add_f32_dpp v88, v64, v64 quad_perm:[1,0,3,2] row_mask:0xf bank_mask:0xf
	s_nop 1
	v_add_f32_dpp v88, v88, v88 quad_perm:[2,3,0,1] row_mask:0xf bank_mask:0xf
	s_nop 1
	v_add_f32_dpp v88, v88, v88 row_half_mirror row_mask:0xf bank_mask:0xf
	s_nop 1
	v_add_f32_dpp v88, v88, v88 row_mirror row_mask:0xf bank_mask:0xf
	s_nop 1
	v_readlane_b32 s48, v88, 0
	v_readlane_b32 s49, v88, 16
	v_readlane_b32 s50, v88, 32
	v_readlane_b32 s51, v88, 48
	s_nop 1
	v_mov_b32_e32 v88, s48
	v_add_f32_e32 v88, s49, v88
	v_add_f32_e32 v88, s50, v88
	v_add_f32_e32 v88, s51, v88
	v_fmamk_f32 v88, v88, 0x3a800000, v16
	v_mul_f32_e32 v89, 0x4b800000, v88
	v_cmp_gt_f32_e64 s[8:9], s3, v88
	s_nop 1
	v_cndmask_b32_e64 v88, v88, v89, s[8:9]
	v_rsq_f32_e32 v88, v88
	s_nop 0
	v_mul_f32_e32 v89, 0x45800000, v88
	v_cndmask_b32_e64 v88, v88, v89, s[8:9]
	v_mul_f32_e32 v32, v32, v88
	v_mul_f32_e32 v33, v33, v88
	v_mul_f32_e32 v34, v34, v88
	v_mul_f32_e32 v35, v35, v88
	v_mul_f32_e32 v36, v36, v88
	v_mul_f32_e32 v37, v37, v88
	v_mul_f32_e32 v38, v38, v88
	v_mul_f32_e32 v39, v39, v88
	v_mul_f32_e32 v40, v40, v88
	v_mul_f32_e32 v41, v41, v88
	v_mul_f32_e32 v42, v42, v88
	v_mul_f32_e32 v43, v43, v88
	v_mul_f32_e32 v44, v44, v88
	v_mul_f32_e32 v45, v45, v88
	v_mul_f32_e32 v46, v46, v88
	v_mul_f32_e32 v47, v47, v88
	v_mul_f32_e32 v32, v0, v32
	v_mul_f32_e32 v33, v1, v33
	v_mul_f32_e32 v34, v2, v34
	v_mul_f32_e32 v35, v3, v35
	v_mul_f32_e32 v36, v4, v36
	v_mul_f32_e32 v37, v5, v37
	v_mul_f32_e32 v38, v6, v38
	v_mul_f32_e32 v39, v7, v39
	v_mul_f32_e32 v40, v8, v40
	v_mul_f32_e32 v41, v9, v41
	v_mul_f32_e32 v42, v10, v42
	v_mul_f32_e32 v43, v11, v43
	v_mul_f32_e32 v44, v12, v44
	v_mul_f32_e32 v45, v13, v45
	v_mul_f32_e32 v46, v14, v46
	v_mul_f32_e32 v47, v15, v47
	s_add_i32 s7, s42, 0
	v_add_u32_e32 v18, s7, v17
	ds_write_b128 v18, v[32:35]
	ds_write_b128 v18, v[36:39] offset:1024
	ds_write_b128 v18, v[40:43] offset:2048
	ds_write_b128 v18, v[44:47] offset:3072
	v_cvt_pk_bf16_f32 v80, v32, v33
	v_cvt_pk_bf16_f32 v81, v34, v35
	v_cvt_pk_bf16_f32 v82, v36, v37
	v_cvt_pk_bf16_f32 v83, v38, v39
	v_cvt_pk_bf16_f32 v84, v40, v41
	v_cvt_pk_bf16_f32 v85, v42, v43
	v_cvt_pk_bf16_f32 v86, v44, v45
	v_cvt_pk_bf16_f32 v87, v46, v47
	global_store_dwordx2 v29, v[80:81], s[40:41]
	global_store_dwordx2 v29, v[82:83], s[40:41] offset:512
	global_store_dwordx2 v29, v[84:85], s[40:41] offset:1024
	global_store_dwordx2 v29, v[86:87], s[40:41] offset:1536
	v_mul_f32_e32 v64, v48, v48
	v_fmac_f32_e32 v64, v49, v49
	v_mul_f32_e32 v65, v50, v50
	v_fmac_f32_e32 v65, v51, v51
	v_add_f32_e32 v64, v64, v65
; #define LAS __attribute__((address_space(3)))
; __device__ __forceinline__ void wave_lds_sync() { asm volatile("s_waitcnt lgkmcnt(0)" ::: "memory"); __builtin_amdgcn_wave_barrier(); }
; __device__ __forceinline__ u32x2 pk4(f32x4 v) { u32x2 w; w.x = cvt_pk_bf16(v[0], v[1]); w.y = cvt_pk_bf16(v[2], v[3]); return w; }
; __device__ __forceinline__ void p0_rows(const Args& a, LAS unsigned char* lds, int gw, int NGW, int wave, int lane, int tid) {
;     ...
;         for (int j = 0; j < 4; ++j) { v[j] = v[j] * rstd * g[j]; ho[64 * j] = pk4(v[j]); *(LAS f32x4*)(hrow + j * 264 + 4 * lane) = v[j]; }
;         wave_lds_sync();
;         const int jj = lane & 15, p = lane >> 4; float acc = 0.f;
;         const LAS float* hp = hrow + p * 264; const LAS float* wp = WdL + p * 4112 + jj;
; #pragma unroll 8
;         for (int kk = 0; kk < 256; ++kk) acc += hp[kk] * wp[kk * 16];
;         acc += __shfl_xor(acc, 16); acc += __shfl_xor(acc, 32);
;         if (lane < 16) DLR[(size_t)row * 16 + jj] = acc;
	v_mul_f32_e32 v66, v52, v52
	v_fmac_f32_e32 v66, v53, v53
	v_mul_f32_e32 v67, v54, v54
	v_fmac_f32_e32 v67, v55, v55
	v_add_f32_e32 v66, v66, v67
	v_mul_f32_e32 v68, v56, v56
	v_fmac_f32_e32 v68, v57, v57
	v_mul_f32_e32 v69, v58, v58
	v_fmac_f32_e32 v69, v59, v59
	v_add_f32_e32 v68, v68, v69
	v_mul_f32_e32 v70, v60, v60
	v_fmac_f32_e32 v70, v61, v61
	v_mul_f32_e32 v71, v62, v62
	v_fmac_f32_e32 v71, v63, v63
	v_add_f32_e32 v70, v70, v71
	v_add_f32_e32 v64, v64, v66
	v_add_f32_e32 v64, v64, v68
	v_add_f32_e32 v64, v64, v70
	s_nop 1
	v_add_f32_dpp v88, v64, v64 quad_perm:[1,0,3,2] row_mask:0xf bank_mask:0xf
	s_nop 1
	v_add_f32_dpp v88, v88, v88 quad_perm:[2,3,0,1] row_mask:0xf bank_mask:0xf
	s_nop 1
	v_add_f32_dpp v88, v88, v88 row_half_mirror row_mask:0xf bank_mask:0xf
	s_nop 1
	v_add_f32_dpp v88, v88, v88 row_mirror row_mask:0xf bank_mask:0xf
	s_nop 1
	v_readlane_b32 s48, v88, 0
	v_readlane_b32 s49, v88, 16
	v_readlane_b32 s50, v88, 32
	v_readlane_b32 s51, v88, 48
	s_nop 1
	v_mov_b32_e32 v88, s48
	v_add_f32_e32 v88, s49, v88
	v_add_f32_e32 v88, s50, v88
	v_add_f32_e32 v88, s51, v88
	v_fmamk_f32 v88, v88, 0x3a800000, v16
	v_mul_f32_e32 v89, 0x4b800000, v88
	v_cmp_gt_f32_e64 s[8:9], s3, v88
	s_nop 1
	v_cndmask_b32_e64 v88, v88, v89, s[8:9]
	v_rsq_f32_e32 v88, v88
	s_nop 0
	v_mul_f32_e32 v89, 0x45800000, v88
	v_cndmask_b32_e64 v88, v88, v89, s[8:9]
	v_mul_f32_e32 v48, v48, v88
	v_mul_f32_e32 v49, v49, v88
	v_mul_f32_e32 v50, v50, v88
	v_mul_f32_e32 v51, v51, v88
	v_mul_f32_e32 v52, v52, v88
	v_mul_f32_e32 v53, v53, v88
	v_mul_f32_e32 v54, v54, v88
	v_mul_f32_e32 v55, v55, v88
	v_mul_f32_e32 v56, v56, v88
	v_mul_f32_e32 v57, v57, v88
	v_mul_f32_e32 v58, v58, v88
	v_mul_f32_e32 v59, v59, v88
	v_mul_f32_e32 v60, v60, v88
	v_mul_f32_e32 v61, v61, v88
	v_mul_f32_e32 v62, v62, v88
	v_mul_f32_e32 v63, v63, v88
	v_mul_f32_e32 v48, v0, v48
	v_mul_f32_e32 v49, v1, v49
	v_mul_f32_e32 v50, v2, v50
	v_mul_f32_e32 v51, v3, v51
	v_mul_f32_e32 v52, v4, v52
	v_mul_f32_e32 v53, v5, v53
	v_mul_f32_e32 v54, v6, v54
	v_mul_f32_e32 v55, v7, v55
	v_mul_f32_e32 v56, v8, v56
	v_mul_f32_e32 v57, v9, v57
	v_mul_f32_e32 v58, v10, v58
	v_mul_f32_e32 v59, v11, v59
	v_mul_f32_e32 v60, v12, v60
	v_mul_f32_e32 v61, v13, v61
	v_mul_f32_e32 v62, v14, v62
	v_mul_f32_e32 v63, v15, v63
	s_add_i32 s7, s42, 32896
	v_add_u32_e32 v18, s7, v17
	ds_write_b128 v18, v[48:51]
	ds_write_b128 v18, v[52:55] offset:1024
	ds_write_b128 v18, v[56:59] offset:2048
	ds_write_b128 v18, v[60:63] offset:3072
	s_add_u32 s10, s40, 0x400000
	s_addc_u32 s11, s41, 0
	v_cvt_pk_bf16_f32 v80, v48, v49
	v_cvt_pk_bf16_f32 v81, v50, v51
	v_cvt_pk_bf16_f32 v82, v52, v53
	v_cvt_pk_bf16_f32 v83, v54, v55
	v_cvt_pk_bf16_f32 v84, v56, v57
	v_cvt_pk_bf16_f32 v85, v58, v59
	v_cvt_pk_bf16_f32 v86, v60, v61
	v_cvt_pk_bf16_f32 v87, v62, v63
	global_store_dwordx2 v29, v[80:81], s[10:11]
	global_store_dwordx2 v29, v[82:83], s[10:11] offset:512
	global_store_dwordx2 v29, v[84:85], s[10:11] offset:1024
	global_store_dwordx2 v29, v[86:87], s[10:11] offset:1536
	s_add_u32 s40, s40, 0x800000
	s_addc_u32 s41, s41, 0
	s_waitcnt lgkmcnt(0)
	s_barrier
	s_waitcnt vmcnt(16)
	ds_read_b128 v[128:131], v19
	ds_read_b128 v[132:135], v19 offset:16
	ds_read_b128 v[136:139], v19 offset:32
	ds_read_b128 v[140:143], v19 offset:48
	ds_read_b128 v[144:147], v19 offset:64
	ds_read_b128 v[148:151], v19 offset:80
	ds_read_b128 v[152:155], v19 offset:96
	ds_read_b128 v[156:159], v19 offset:112
	s_waitcnt lgkmcnt(7)
	v_mfma_f32_16x16x4_f32 v[160:163], v128, v96, 0
	v_mfma_f32_16x16x4_f32 v[164:167], v129, v97, 0
	v_mfma_f32_16x16x4_f32 v[160:163], v130, v98, v[160:163]
	v_mfma_f32_16x16x4_f32 v[164:167], v131, v99, v[164:167]
	s_waitcnt lgkmcnt(6)
	v_mfma_f32_16x16x4_f32 v[160:163], v132, v100, v[160:163]
	v_mfma_f32_16x16x4_f32 v[164:167], v133, v101, v[164:167]
	v_mfma_f32_16x16x4_f32 v[160:163], v134, v102, v[160:163]
	v_mfma_f32_16x16x4_f32 v[164:167], v135, v103, v[164:167]
	s_waitcnt lgkmcnt(5)
	v_mfma_f32_16x16x4_f32 v[160:163], v136, v104, v[160:163]
	v_mfma_f32_16x16x4_f32 v[164:167], v137, v105, v[164:167]
	v_mfma_f32_16x16x4_f32 v[160:163], v138, v106, v[160:163]
	v_mfma_f32_16x16x4_f32 v[164:167], v139, v107, v[164:167]
	s_waitcnt lgkmcnt(4)
	v_mfma_f32_16x16x4_f32 v[160:163], v140, v108, v[160:163]
	v_mfma_f32_16x16x4_f32 v[164:167], v141, v109, v[164:167]
	v_mfma_f32_16x16x4_f32 v[160:163], v142, v110, v[160:163]
	v_mfma_f32_16x16x4_f32 v[164:167], v143, v111, v[164:167]
	s_waitcnt lgkmcnt(3)
	v_mfma_f32_16x16x4_f32 v[160:163], v144, v112, v[160:163]
	v_mfma_f32_16x16x4_f32 v[164:167], v145, v113, v[164:167]
	v_mfma_f32_16x16x4_f32 v[160:163], v146, v114, v[160:163]
	v_mfma_f32_16x16x4_f32 v[164:167], v147, v115, v[164:167]
	s_waitcnt lgkmcnt(2)
	v_mfma_f32_16x16x4_f32 v[160:163], v148, v116, v[160:163]
	v_mfma_f32_16x16x4_f32 v[164:167], v149, v117, v[164:167]
	v_mfma_f32_16x16x4_f32 v[160:163], v150, v118, v[160:163]
	v_mfma_f32_16x16x4_f32 v[164:167], v151, v119, v[164:167]
	s_waitcnt lgkmcnt(1)
	v_mfma_f32_16x16x4_f32 v[160:163], v152, v120, v[160:163]
	v_mfma_f32_16x16x4_f32 v[164:167], v153, v121, v[164:167]
	v_mfma_f32_16x16x4_f32 v[160:163], v154, v122, v[160:163]
	v_mfma_f32_16x16x4_f32 v[164:167], v155, v123, v[164:167]
	s_waitcnt lgkmcnt(0)
	v_mfma_f32_16x16x4_f32 v[160:163], v156, v124, v[160:163]
	v_mfma_f32_16x16x4_f32 v[164:167], v157, v125, v[164:167]
	v_mfma_f32_16x16x4_f32 v[160:163], v158, v126, v[160:163]
	v_mfma_f32_16x16x4_f32 v[164:167], v159, v127, v[164:167]
	s_nop 9
	v_add_f32_e32 v160, v160, v164
	v_add_f32_e32 v161, v161, v165
	v_add_f32_e32 v162, v162, v166
	v_add_f32_e32 v163, v163, v167
	ds_write_b128 v21, v[160:163]
	s_waitcnt lgkmcnt(0)
	s_barrier
	s_cmp_lt_u32 s93, 4
	s_cbranch_scc0 .Lp0m_s3skip_b0
	ds_read_b32 v168, v22
	ds_read_b32 v169, v22 offset:1024
	ds_read_b32 v170, v22 offset:2048
	ds_read_b32 v171, v22 offset:3072
	ds_read_b32 v172, v22 offset:4096
	ds_read_b32 v173, v22 offset:5120
	ds_read_b32 v174, v22 offset:6144
	ds_read_b32 v175, v22 offset:7168
	s_waitcnt lgkmcnt(6)
	v_add_f32_e32 v168, v168, v169
	s_waitcnt lgkmcnt(5)
	v_add_f32_e32 v168, v168, v170
	s_waitcnt lgkmcnt(4)
	v_add_f32_e32 v168, v168, v171
	s_waitcnt lgkmcnt(3)
	v_add_f32_e32 v168, v168, v172
	s_waitcnt lgkmcnt(2)
	v_add_f32_e32 v168, v168, v173
	s_waitcnt lgkmcnt(1)
	v_add_f32_e32 v168, v168, v174
	s_waitcnt lgkmcnt(0)
	v_add_f32_e32 v168, v168, v175
	global_store_dword v23, v168, s[52:53]
